# v46 + kernel-wide static s_setprio 1 for waves 4-7
# baseline (speedup 1.0000x reference)
_Z6mk_fwd4Args:
	s_mov_b64 s[72:73], s[0:1]
	s_load_dword s56, s[0:1], 0x130
	s_add_u32 s0, s72, 0x130
	s_addc_u32 s1, s73, 0
	v_and_b32_e32 v208, 0x3ff, v0
	v_readfirstlane_b32 s98, v208
	s_bitcmp1_b32 s98, 8
	s_cbranch_scc0 .Lsp_entry
	s_setprio 1
.Lsp_entry:
	v_writelane_b32 v253, s0, 0
	s_mov_b32 s96, s2
	v_cmp_gt_u32_e32 vcc, 2, v208
	v_writelane_b32 v253, s1, 1
	s_and_saveexec_b64 s[0:1], vcc
	v_lshl_add_u32 v1, v208, 2, 0
	v_add_u32_e32 v1, 0x23fc0, v1
	v_mov_b32_e32 v2, 0
	ds_write_b32 v1, v2
	s_or_b64 exec, exec, s[0:1]
	s_waitcnt lgkmcnt(0)
	s_barrier
	s_load_dwordx2 s[0:1], s[72:73], 0x120
	s_getreg_b32 s4, hwreg(HW_REG_XCC_ID, 0, 4)
	v_cmp_eq_u32_e64 s[6:7], 0, v208
	s_waitcnt lgkmcnt(0)
	s_add_u32 s2, s0, 0x80000
	s_addc_u32 s3, s1, 0
	s_and_b32 s9, s4, 15
	s_mov_b64 s[4:5], exec
	v_writelane_b32 v253, s6, 2
	s_nop 1
	v_writelane_b32 v253, s7, 3
	s_and_b64 s[6:7], s[4:5], s[6:7]
	s_mov_b64 exec, s[6:7]
	s_cbranch_execz .LBB0_5
	s_mov_b64 s[6:7], exec
	v_mbcnt_lo_u32_b32 v1, s6, 0
	v_mbcnt_hi_u32_b32 v1, s7, v1
	v_cmp_eq_u32_e32 vcc, 0, v1
	s_and_b64 s[10:11], exec, vcc
	s_mov_b64 exec, s[10:11]
	s_cbranch_execz .LBB0_5
	s_lshl_b32 s8, s9, 8
	s_bcnt1_i32_b64 s6, s[6:7]
	v_mov_b32_e32 v1, s8
	v_mov_b32_e32 v2, s6
	global_atomic_add v1, v2, s[2:3] offset:1024
